# S5 out task: direction 1's first 16 prefix entries requested before direction 0's scan (lands under scan + C projection)
# speedup vs baseline: 1.0934x; 1.0030x over previous
.Ls5o_nostatea:
.Ls5o_d1skip:
	s_cmp_eq_u32 s56, 1
	s_cbranch_scc1 .Ls5o_pre1
	s_mov_b32 s57, s38
	s_mov_b32 s100, s54
	s_lshl_b32 s100, s100, 4
	s_add_u32 s100, s100, s99
	s_lshl_b32 s100, s100, 1
	s_lshl_b32 s100, s100, 9
	s_add_u32 s100, s100, 0xcba4000
	s_add_u32 s50, s96, s100
	s_addc_u32 s51, s97, 0
	s_mov_b32 s58, 0x4000
	s_mov_b32 s59, 0
	s_cmp_le_u32 s57, 0
	s_cbranch_scc1 .Ls5o_ei0
	global_load_dwordx2 v[84:85], v10, s[50:51]
	s_add_u32 s50, s50, s58
	s_addc_u32 s51, s51, s59
	s_cmp_le_u32 s57, 1
	s_cbranch_scc1 .Ls5o_ei0
	global_load_dwordx2 v[86:87], v10, s[50:51]
	s_add_u32 s50, s50, s58
	s_addc_u32 s51, s51, s59
	s_cmp_le_u32 s57, 2
	s_cbranch_scc1 .Ls5o_ei0
	global_load_dwordx2 v[88:89], v10, s[50:51]
	s_add_u32 s50, s50, s58
	s_addc_u32 s51, s51, s59
	s_cmp_le_u32 s57, 3
	s_cbranch_scc1 .Ls5o_ei0
	global_load_dwordx2 v[90:91], v10, s[50:51]
	s_add_u32 s50, s50, s58
	s_addc_u32 s51, s51, s59
	s_cmp_le_u32 s57, 4
	s_cbranch_scc1 .Ls5o_ei0
	global_load_dwordx2 v[92:93], v10, s[50:51]
	s_add_u32 s50, s50, s58
	s_addc_u32 s51, s51, s59
	s_cmp_le_u32 s57, 5
	s_cbranch_scc1 .Ls5o_ei0
	global_load_dwordx2 v[94:95], v10, s[50:51]
	s_add_u32 s50, s50, s58
	s_addc_u32 s51, s51, s59
	s_cmp_le_u32 s57, 6
	s_cbranch_scc1 .Ls5o_ei0
	global_load_dwordx2 v[96:97], v10, s[50:51]
	s_add_u32 s50, s50, s58
	s_addc_u32 s51, s51, s59
	s_cmp_le_u32 s57, 7
	s_cbranch_scc1 .Ls5o_ei0
	global_load_dwordx2 v[98:99], v10, s[50:51]
	s_add_u32 s50, s50, s58
	s_addc_u32 s51, s51, s59
	s_cmp_le_u32 s57, 8
	s_cbranch_scc1 .Ls5o_ei0
	global_load_dwordx2 v[100:101], v10, s[50:51]
	s_add_u32 s50, s50, s58
	s_addc_u32 s51, s51, s59
	s_cmp_le_u32 s57, 9
	s_cbranch_scc1 .Ls5o_ei0
	global_load_dwordx2 v[102:103], v10, s[50:51]
	s_add_u32 s50, s50, s58
	s_addc_u32 s51, s51, s59
	s_cmp_le_u32 s57, 10
	s_cbranch_scc1 .Ls5o_ei0
	global_load_dwordx2 v[104:105], v10, s[50:51]
	s_add_u32 s50, s50, s58
	s_addc_u32 s51, s51, s59
	s_cmp_le_u32 s57, 11
	s_cbranch_scc1 .Ls5o_ei0
	global_load_dwordx2 v[106:107], v10, s[50:51]
	s_add_u32 s50, s50, s58
	s_addc_u32 s51, s51, s59
	s_cmp_le_u32 s57, 12
	s_cbranch_scc1 .Ls5o_ei0
	global_load_dwordx2 v[108:109], v10, s[50:51]
	s_add_u32 s50, s50, s58
	s_addc_u32 s51, s51, s59
	s_cmp_le_u32 s57, 13
	s_cbranch_scc1 .Ls5o_ei0
	global_load_dwordx2 v[110:111], v10, s[50:51]
	s_add_u32 s50, s50, s58
	s_addc_u32 s51, s51, s59
	s_cmp_le_u32 s57, 14
	s_cbranch_scc1 .Ls5o_ei0
	global_load_dwordx2 v[112:113], v10, s[50:51]
	s_add_u32 s50, s50, s58
	s_addc_u32 s51, s51, s59
	s_cmp_le_u32 s57, 15
	s_cbranch_scc1 .Ls5o_ei0
	global_load_dwordx2 v[114:115], v10, s[50:51]
	s_add_u32 s50, s50, s58
	s_addc_u32 s51, s51, s59
.Ls5o_ei0:
.Ls5o_pre1:
	s_waitcnt vmcnt(0)
	s_cmp_lg_u32 s56, 1
	s_cbranch_scc1 .Ls5o_nocopy
	v_mov_b32_e32 v44, v20
	v_mov_b32_e32 v45, v21
	v_mov_b32_e32 v46, v22
	v_mov_b32_e32 v47, v23
	v_mov_b32_e32 v48, v24
	v_mov_b32_e32 v49, v25
	v_mov_b32_e32 v50, v26
	v_mov_b32_e32 v51, v27
	v_mov_b32_e32 v52, v28
	v_mov_b32_e32 v53, v29
	v_mov_b32_e32 v54, v30
	v_mov_b32_e32 v55, v31
	v_mov_b32_e32 v56, v32
	v_mov_b32_e32 v57, v33
	v_mov_b32_e32 v58, v34
	v_mov_b32_e32 v59, v35
	v_mov_b32_e32 v60, v190
	v_mov_b32_e32 v61, v191
	v_mov_b32_e32 v62, v192
	v_mov_b32_e32 v63, v193
	v_mov_b32_e32 v64, v200
	v_mov_b32_e32 v65, v201
	v_mov_b32_e32 v66, v202
	v_mov_b32_e32 v67, v203
	v_mov_b32_e32 v68, v222
	v_mov_b32_e32 v69, v223
	v_mov_b32_e32 v70, v224
	v_mov_b32_e32 v71, v225
	v_mov_b32_e32 v72, v226
	v_mov_b32_e32 v73, v227
	v_mov_b32_e32 v74, v228
	v_mov_b32_e32 v75, v229
	v_mov_b32_e32 v76, v230
	v_mov_b32_e32 v77, v231
	v_mov_b32_e32 v78, v232
	v_mov_b32_e32 v79, v233
	v_mov_b32_e32 v80, v194
	v_mov_b32_e32 v81, v195
	v_mov_b32_e32 v82, v173
	v_mov_b32_e32 v83, v197

.Ls5o_pfdone:
	s_cmp_eq_u32 s56, 1
	s_cbranch_scc1 .Ls5o_nopre
	s_sub_u32 s57, s39, 1
	s_sub_u32 s57, s57, s38
	s_add_u32 s100, s54, s39
	s_sub_u32 s100, s100, 1
	s_lshl_b32 s100, s100, 4
	s_add_u32 s100, s100, s99
	s_lshl_b32 s100, s100, 1
	s_add_u32 s100, s100, 1
	s_lshl_b32 s100, s100, 9
	s_add_u32 s100, s100, 0xcba4000
	s_add_u32 s50, s96, s100
	s_addc_u32 s51, s97, 0
	s_mov_b32 s58, 0xffffc000
	s_mov_b32 s59, -1
	s_cmp_le_u32 s57, 0
	s_cbranch_scc1 .Ls5o_ei4
	global_load_dwordx2 v[84:85], v10, s[50:51]
	s_add_u32 s50, s50, s58
	s_addc_u32 s51, s51, s59
	s_cmp_le_u32 s57, 1
	s_cbranch_scc1 .Ls5o_ei4
	global_load_dwordx2 v[86:87], v10, s[50:51]
	s_add_u32 s50, s50, s58
	s_addc_u32 s51, s51, s59
	s_cmp_le_u32 s57, 2
	s_cbranch_scc1 .Ls5o_ei4
	global_load_dwordx2 v[88:89], v10, s[50:51]
	s_add_u32 s50, s50, s58
	s_addc_u32 s51, s51, s59
	s_cmp_le_u32 s57, 3
	s_cbranch_scc1 .Ls5o_ei4
	global_load_dwordx2 v[90:91], v10, s[50:51]
	s_add_u32 s50, s50, s58
	s_addc_u32 s51, s51, s59
	s_cmp_le_u32 s57, 4
	s_cbranch_scc1 .Ls5o_ei4
	global_load_dwordx2 v[92:93], v10, s[50:51]
	s_add_u32 s50, s50, s58
	s_addc_u32 s51, s51, s59
	s_cmp_le_u32 s57, 5
	s_cbranch_scc1 .Ls5o_ei4
	global_load_dwordx2 v[94:95], v10, s[50:51]
	s_add_u32 s50, s50, s58
	s_addc_u32 s51, s51, s59
	s_cmp_le_u32 s57, 6
	s_cbranch_scc1 .Ls5o_ei4
	global_load_dwordx2 v[96:97], v10, s[50:51]
	s_add_u32 s50, s50, s58
	s_addc_u32 s51, s51, s59
	s_cmp_le_u32 s57, 7
	s_cbranch_scc1 .Ls5o_ei4
	global_load_dwordx2 v[98:99], v10, s[50:51]
	s_add_u32 s50, s50, s58
	s_addc_u32 s51, s51, s59
	s_cmp_le_u32 s57, 8
	s_cbranch_scc1 .Ls5o_ei4
	global_load_dwordx2 v[100:101], v10, s[50:51]
	s_add_u32 s50, s50, s58
	s_addc_u32 s51, s51, s59
	s_cmp_le_u32 s57, 9
	s_cbranch_scc1 .Ls5o_ei4
	global_load_dwordx2 v[102:103], v10, s[50:51]
	s_add_u32 s50, s50, s58
	s_addc_u32 s51, s51, s59
	s_cmp_le_u32 s57, 10
	s_cbranch_scc1 .Ls5o_ei4
	global_load_dwordx2 v[104:105], v10, s[50:51]
	s_add_u32 s50, s50, s58
	s_addc_u32 s51, s51, s59
	s_cmp_le_u32 s57, 11
	s_cbranch_scc1 .Ls5o_ei4
	global_load_dwordx2 v[106:107], v10, s[50:51]
	s_add_u32 s50, s50, s58
	s_addc_u32 s51, s51, s59
	s_cmp_le_u32 s57, 12
	s_cbranch_scc1 .Ls5o_ei4
	global_load_dwordx2 v[108:109], v10, s[50:51]
	s_add_u32 s50, s50, s58
	s_addc_u32 s51, s51, s59
	s_cmp_le_u32 s57, 13
	s_cbranch_scc1 .Ls5o_ei4
	global_load_dwordx2 v[110:111], v10, s[50:51]
	s_add_u32 s50, s50, s58
	s_addc_u32 s51, s51, s59
	s_cmp_le_u32 s57, 14
	s_cbranch_scc1 .Ls5o_ei4
	global_load_dwordx2 v[112:113], v10, s[50:51]
	s_add_u32 s50, s50, s58
	s_addc_u32 s51, s51, s59
	s_cmp_le_u32 s57, 15
	s_cbranch_scc1 .Ls5o_ei4
	global_load_dwordx2 v[114:115], v10, s[50:51]
	s_add_u32 s50, s50, s58
	s_addc_u32 s51, s51, s59
.Ls5o_ei4:
.Ls5o_nopre:
	s_cmp_eq_u32 s56, 0
	s_cselect_b32 s100, 0, 16368
	s_mov_b32 s101, 0xfffffdf0
	s_cselect_b32 s101, 528, s101
	v_add_u32_e32 v15, s100, v7
	v_mov_b32_e32 v16, v15
	s_waitcnt lgkmcnt(0)
	ds_read_b64 v[132:133], v15
	v_add_u32_e32 v15, s101, v15
	ds_read_b64 v[134:135], v15
	v_add_u32_e32 v15, s101, v15
	ds_read_b64 v[136:137], v15
	v_add_u32_e32 v15, s101, v15
	ds_read_b64 v[138:139], v15
	v_add_u32_e32 v15, s101, v15
	ds_read_b64 v[140:141], v15
	v_add_u32_e32 v15, s101, v15
	ds_read_b64 v[142:143], v15
	v_add_u32_e32 v15, s101, v15
	ds_read_b64 v[144:145], v15
	v_add_u32_e32 v15, s101, v15
	ds_read_b64 v[146:147], v15
	v_add_u32_e32 v15, s101, v15
	s_waitcnt lgkmcnt(7)
	v_mul_f32_e32 v184, v77, v183
	v_mul_f32_e32 v185, v77, v182
	v_fma_f32 v0, v76, v182, -v184
	v_fma_f32 v1, v76, v183, v185
	v_add_f32_e32 v182, v0, v132
	v_add_f32_e32 v183, v1, v133
	ds_write_b64 v16, v[182:183]
	v_add_u32_e32 v16, s101, v16
	ds_read_b64 v[132:133], v15
	v_add_u32_e32 v15, s101, v15
	s_waitcnt lgkmcnt(8)
	v_mul_f32_e32 v184, v77, v183
	v_mul_f32_e32 v185, v77, v182
	v_fma_f32 v0, v76, v182, -v184
	v_fma_f32 v1, v76, v183, v185
	v_add_f32_e32 v182, v0, v134
	v_add_f32_e32 v183, v1, v135
	ds_write_b64 v16, v[182:183]
	v_add_u32_e32 v16, s101, v16
	ds_read_b64 v[134:135], v15
	v_add_u32_e32 v15, s101, v15
	s_waitcnt lgkmcnt(9)
	v_mul_f32_e32 v184, v77, v183
	v_mul_f32_e32 v185, v77, v182
	v_fma_f32 v0, v76, v182, -v184
	v_fma_f32 v1, v76, v183, v185
	v_add_f32_e32 v182, v0, v136
	v_add_f32_e32 v183, v1, v137
	ds_write_b64 v16, v[182:183]
	v_add_u32_e32 v16, s101, v16
	ds_read_b64 v[136:137], v15
	v_add_u32_e32 v15, s101, v15
	s_waitcnt lgkmcnt(10)
	v_mul_f32_e32 v184, v77, v183
	v_mul_f32_e32 v185, v77, v182
	v_fma_f32 v0, v76, v182, -v184
	v_fma_f32 v1, v76, v183, v185
	v_add_f32_e32 v182, v0, v138
	v_add_f32_e32 v183, v1, v139
	ds_write_b64 v16, v[182:183]
	v_add_u32_e32 v16, s101, v16
	ds_read_b64 v[138:139], v15
	v_add_u32_e32 v15, s101, v15
	s_waitcnt lgkmcnt(11)
	v_mul_f32_e32 v184, v77, v183
	v_mul_f32_e32 v185, v77, v182
	v_fma_f32 v0, v76, v182, -v184
	v_fma_f32 v1, v76, v183, v185
	v_add_f32_e32 v182, v0, v140
	v_add_f32_e32 v183, v1, v141
	ds_write_b64 v16, v[182:183]
	v_add_u32_e32 v16, s101, v16
	ds_read_b64 v[140:141], v15
	v_add_u32_e32 v15, s101, v15
	s_waitcnt lgkmcnt(12)
	v_mul_f32_e32 v184, v77, v183
	v_mul_f32_e32 v185, v77, v182
	v_fma_f32 v0, v76, v182, -v184
	v_fma_f32 v1, v76, v183, v185
	v_add_f32_e32 v182, v0, v142
	v_add_f32_e32 v183, v1, v143
	ds_write_b64 v16, v[182:183]
	v_add_u32_e32 v16, s101, v16
	ds_read_b64 v[142:143], v15
	v_add_u32_e32 v15, s101, v15
	s_waitcnt lgkmcnt(13)
	v_mul_f32_e32 v184, v77, v183
	v_mul_f32_e32 v185, v77, v182
	v_fma_f32 v0, v76, v182, -v184
	v_fma_f32 v1, v76, v183, v185
	v_add_f32_e32 v182, v0, v144
	v_add_f32_e32 v183, v1, v145
	ds_write_b64 v16, v[182:183]
	v_add_u32_e32 v16, s101, v16
	ds_read_b64 v[144:145], v15
	v_add_u32_e32 v15, s101, v15
	s_waitcnt lgkmcnt(14)
	v_mul_f32_e32 v184, v77, v183
	v_mul_f32_e32 v185, v77, v182
	v_fma_f32 v0, v76, v182, -v184
	v_fma_f32 v1, v76, v183, v185
	v_add_f32_e32 v182, v0, v146
	v_add_f32_e32 v183, v1, v147
	ds_write_b64 v16, v[182:183]
	v_add_u32_e32 v16, s101, v16
	ds_read_b64 v[146:147], v15
	v_add_u32_e32 v15, s101, v15
	s_waitcnt lgkmcnt(14)
	v_mul_f32_e32 v184, v77, v183
	v_mul_f32_e32 v185, v77, v182
	v_fma_f32 v0, v76, v182, -v184
	v_fma_f32 v1, v76, v183, v185
	v_add_f32_e32 v182, v0, v132
	v_add_f32_e32 v183, v1, v133
	ds_write_b64 v16, v[182:183]
	v_add_u32_e32 v16, s101, v16
	ds_read_b64 v[132:133], v15
	v_add_u32_e32 v15, s101, v15
	s_waitcnt lgkmcnt(14)
	v_mul_f32_e32 v184, v77, v183
	v_mul_f32_e32 v185, v77, v182
	v_fma_f32 v0, v76, v182, -v184
	v_fma_f32 v1, v76, v183, v185
	v_add_f32_e32 v182, v0, v134
	v_add_f32_e32 v183, v1, v135
	ds_write_b64 v16, v[182:183]
	v_add_u32_e32 v16, s101, v16
	ds_read_b64 v[134:135], v15
	v_add_u32_e32 v15, s101, v15
	s_waitcnt lgkmcnt(14)
	v_mul_f32_e32 v184, v77, v183
	v_mul_f32_e32 v185, v77, v182
	v_fma_f32 v0, v76, v182, -v184
	v_fma_f32 v1, v76, v183, v185
	v_add_f32_e32 v182, v0, v136
	v_add_f32_e32 v183, v1, v137
	ds_write_b64 v16, v[182:183]
	v_add_u32_e32 v16, s101, v16
	ds_read_b64 v[136:137], v15
	v_add_u32_e32 v15, s101, v15
	s_waitcnt lgkmcnt(14)
	v_mul_f32_e32 v184, v77, v183
	v_mul_f32_e32 v185, v77, v182
	v_fma_f32 v0, v76, v182, -v184
	v_fma_f32 v1, v76, v183, v185
	v_add_f32_e32 v182, v0, v138
	v_add_f32_e32 v183, v1, v139
	ds_write_b64 v16, v[182:183]
	v_add_u32_e32 v16, s101, v16
	ds_read_b64 v[138:139], v15
	v_add_u32_e32 v15, s101, v15
	s_waitcnt lgkmcnt(14)
	v_mul_f32_e32 v184, v77, v183
	v_mul_f32_e32 v185, v77, v182
	v_fma_f32 v0, v76, v182, -v184
	v_fma_f32 v1, v76, v183, v185
	v_add_f32_e32 v182, v0, v140
	v_add_f32_e32 v183, v1, v141
	ds_write_b64 v16, v[182:183]
	v_add_u32_e32 v16, s101, v16
	ds_read_b64 v[140:141], v15
	v_add_u32_e32 v15, s101, v15
	s_waitcnt lgkmcnt(14)
	v_mul_f32_e32 v184, v77, v183
	v_mul_f32_e32 v185, v77, v182
	v_fma_f32 v0, v76, v182, -v184
	v_fma_f32 v1, v76, v183, v185
	v_add_f32_e32 v182, v0, v142
	v_add_f32_e32 v183, v1, v143
	ds_write_b64 v16, v[182:183]
	v_add_u32_e32 v16, s101, v16
	ds_read_b64 v[142:143], v15
	v_add_u32_e32 v15, s101, v15
	s_waitcnt lgkmcnt(14)
	v_mul_f32_e32 v184, v77, v183
	v_mul_f32_e32 v185, v77, v182
	v_fma_f32 v0, v76, v182, -v184
	v_fma_f32 v1, v76, v183, v185
	v_add_f32_e32 v182, v0, v144
	v_add_f32_e32 v183, v1, v145
	ds_write_b64 v16, v[182:183]
	v_add_u32_e32 v16, s101, v16
	ds_read_b64 v[144:145], v15
	v_add_u32_e32 v15, s101, v15
	s_waitcnt lgkmcnt(14)
	v_mul_f32_e32 v184, v77, v183
	v_mul_f32_e32 v185, v77, v182
	v_fma_f32 v0, v76, v182, -v184
	v_fma_f32 v1, v76, v183, v185
	v_add_f32_e32 v182, v0, v146
	v_add_f32_e32 v183, v1, v147
	ds_write_b64 v16, v[182:183]
	v_add_u32_e32 v16, s101, v16
	ds_read_b64 v[146:147], v15
	v_add_u32_e32 v15, s101, v15
	s_waitcnt lgkmcnt(14)
	v_mul_f32_e32 v184, v77, v183
	v_mul_f32_e32 v185, v77, v182
	v_fma_f32 v0, v76, v182, -v184
	v_fma_f32 v1, v76, v183, v185
	v_add_f32_e32 v182, v0, v132
	v_add_f32_e32 v183, v1, v133
	ds_write_b64 v16, v[182:183]
	v_add_u32_e32 v16, s101, v16
	ds_read_b64 v[132:133], v15
	v_add_u32_e32 v15, s101, v15
	s_waitcnt lgkmcnt(14)
	v_mul_f32_e32 v184, v77, v183
	v_mul_f32_e32 v185, v77, v182
	v_fma_f32 v0, v76, v182, -v184
	v_fma_f32 v1, v76, v183, v185
	v_add_f32_e32 v182, v0, v134
	v_add_f32_e32 v183, v1, v135
	ds_write_b64 v16, v[182:183]
	v_add_u32_e32 v16, s101, v16
	ds_read_b64 v[134:135], v15
	v_add_u32_e32 v15, s101, v15
	s_waitcnt lgkmcnt(14)
	v_mul_f32_e32 v184, v77, v183
	v_mul_f32_e32 v185, v77, v182
	v_fma_f32 v0, v76, v182, -v184
	v_fma_f32 v1, v76, v183, v185
	v_add_f32_e32 v182, v0, v136
	v_add_f32_e32 v183, v1, v137
	ds_write_b64 v16, v[182:183]
	v_add_u32_e32 v16, s101, v16
	ds_read_b64 v[136:137], v15
	v_add_u32_e32 v15, s101, v15
	s_waitcnt lgkmcnt(14)
	v_mul_f32_e32 v184, v77, v183
	v_mul_f32_e32 v185, v77, v182
	v_fma_f32 v0, v76, v182, -v184
	v_fma_f32 v1, v76, v183, v185
	v_add_f32_e32 v182, v0, v138
	v_add_f32_e32 v183, v1, v139
	ds_write_b64 v16, v[182:183]
	v_add_u32_e32 v16, s101, v16
	ds_read_b64 v[138:139], v15
	v_add_u32_e32 v15, s101, v15
	s_waitcnt lgkmcnt(14)
	v_mul_f32_e32 v184, v77, v183
	v_mul_f32_e32 v185, v77, v182
	v_fma_f32 v0, v76, v182, -v184
	v_fma_f32 v1, v76, v183, v185
	v_add_f32_e32 v182, v0, v140
	v_add_f32_e32 v183, v1, v141
	ds_write_b64 v16, v[182:183]
	v_add_u32_e32 v16, s101, v16
	ds_read_b64 v[140:141], v15
	v_add_u32_e32 v15, s101, v15
	s_waitcnt lgkmcnt(14)
	v_mul_f32_e32 v184, v77, v183
	v_mul_f32_e32 v185, v77, v182
	v_fma_f32 v0, v76, v182, -v184
	v_fma_f32 v1, v76, v183, v185
	v_add_f32_e32 v182, v0, v142
	v_add_f32_e32 v183, v1, v143
	ds_write_b64 v16, v[182:183]
	v_add_u32_e32 v16, s101, v16
	ds_read_b64 v[142:143], v15
	v_add_u32_e32 v15, s101, v15
	s_waitcnt lgkmcnt(14)
	v_mul_f32_e32 v184, v77, v183
	v_mul_f32_e32 v185, v77, v182
	v_fma_f32 v0, v76, v182, -v184
	v_fma_f32 v1, v76, v183, v185
	v_add_f32_e32 v182, v0, v144
	v_add_f32_e32 v183, v1, v145
	ds_write_b64 v16, v[182:183]
	v_add_u32_e32 v16, s101, v16
	ds_read_b64 v[144:145], v15
	v_add_u32_e32 v15, s101, v15
	s_waitcnt lgkmcnt(14)
	v_mul_f32_e32 v184, v77, v183
	v_mul_f32_e32 v185, v77, v182
	v_fma_f32 v0, v76, v182, -v184
	v_fma_f32 v1, v76, v183, v185
	v_add_f32_e32 v182, v0, v146
	v_add_f32_e32 v183, v1, v147
	ds_write_b64 v16, v[182:183]
	v_add_u32_e32 v16, s101, v16
	ds_read_b64 v[146:147], v15
	v_add_u32_e32 v15, s101, v15
	s_waitcnt lgkmcnt(14)
	v_mul_f32_e32 v184, v77, v183
	v_mul_f32_e32 v185, v77, v182
	v_fma_f32 v0, v76, v182, -v184
	v_fma_f32 v1, v76, v183, v185
	v_add_f32_e32 v182, v0, v132
	v_add_f32_e32 v183, v1, v133
	ds_write_b64 v16, v[182:183]
	v_add_u32_e32 v16, s101, v16
	s_waitcnt lgkmcnt(13)
	v_mul_f32_e32 v184, v77, v183
	v_mul_f32_e32 v185, v77, v182
	v_fma_f32 v0, v76, v182, -v184
	v_fma_f32 v1, v76, v183, v185
	v_add_f32_e32 v182, v0, v134
	v_add_f32_e32 v183, v1, v135
	ds_write_b64 v16, v[182:183]
	v_add_u32_e32 v16, s101, v16
	s_waitcnt lgkmcnt(12)
	v_mul_f32_e32 v184, v77, v183
	v_mul_f32_e32 v185, v77, v182
	v_fma_f32 v0, v76, v182, -v184
	v_fma_f32 v1, v76, v183, v185
	v_add_f32_e32 v182, v0, v136
	v_add_f32_e32 v183, v1, v137
	ds_write_b64 v16, v[182:183]
	v_add_u32_e32 v16, s101, v16
	s_waitcnt lgkmcnt(11)
	v_mul_f32_e32 v184, v77, v183
	v_mul_f32_e32 v185, v77, v182
	v_fma_f32 v0, v76, v182, -v184
	v_fma_f32 v1, v76, v183, v185
	v_add_f32_e32 v182, v0, v138
	v_add_f32_e32 v183, v1, v139
	ds_write_b64 v16, v[182:183]
	v_add_u32_e32 v16, s101, v16
	s_waitcnt lgkmcnt(10)
	v_mul_f32_e32 v184, v77, v183
	v_mul_f32_e32 v185, v77, v182
	v_fma_f32 v0, v76, v182, -v184
	v_fma_f32 v1, v76, v183, v185
	v_add_f32_e32 v182, v0, v140
	v_add_f32_e32 v183, v1, v141
	ds_write_b64 v16, v[182:183]
	v_add_u32_e32 v16, s101, v16
	s_waitcnt lgkmcnt(9)
	v_mul_f32_e32 v184, v77, v183
	v_mul_f32_e32 v185, v77, v182
	v_fma_f32 v0, v76, v182, -v184
	v_fma_f32 v1, v76, v183, v185
	v_add_f32_e32 v182, v0, v142
	v_add_f32_e32 v183, v1, v143
	ds_write_b64 v16, v[182:183]
	v_add_u32_e32 v16, s101, v16
	s_waitcnt lgkmcnt(8)
	v_mul_f32_e32 v184, v77, v183
	v_mul_f32_e32 v185, v77, v182
	v_fma_f32 v0, v76, v182, -v184
	v_fma_f32 v1, v76, v183, v185
	v_add_f32_e32 v182, v0, v144
	v_add_f32_e32 v183, v1, v145
	ds_write_b64 v16, v[182:183]
	v_add_u32_e32 v16, s101, v16
	s_waitcnt lgkmcnt(7)
	v_mul_f32_e32 v184, v77, v183
	v_mul_f32_e32 v185, v77, v182
	v_fma_f32 v0, v76, v182, -v184
	v_fma_f32 v1, v76, v183, v185
	v_add_f32_e32 v182, v0, v146
	v_add_f32_e32 v183, v1, v147
	ds_write_b64 v16, v[182:183]
	v_add_u32_e32 v16, s101, v16
	s_cmp_lg_u32 s55, 0
	s_cbranch_scc1 .Ls5o_nofinal
	s_sub_u32 s100, s39, 1
	s_cmp_eq_u32 s56, 0
	s_cselect_b32 s100, s100, 0
	s_cmp_lg_u32 s38, s100
	s_cbranch_scc1 .Ls5o_nofinal
	v_readlane_b32 s48, v237, 7
	v_readlane_b32 s49, v237, 8
	s_lshl_b32 s100, s47, 1
	s_add_u32 s100, s100, s36
	s_lshl_b32 s100, s100, 1
	s_add_u32 s100, s100, s56
	s_lshl_b32 s100, s100, 4
	s_add_u32 s100, s100, s99
	s_lshl_b32 s100, s100, 8
	v_lshl_add_u32 v184, v3, 2, s100
	v_add_u32_e32 v185, 0x2840000, v184
	v_add_u32_e32 v184, 0x2800000, v184
	global_store_dword v184, v182, s[48:49]
	global_store_dword v185, v183, s[48:49]
